# v025_sleep_plain
# baseline (speedup 1.0000x reference)
; __device__ __forceinline__ void phase_gemm1(const Params& p, int layer, int rep) {
;     ...
;       const float sc = (feat0 >= OFF_Q && feat0 < OFF_K) ? QSCALE : 1.f;
;       char* cl = smem;
; #pragma unroll
;       for (int ai = 0; ai < 2; ++ai)
; #pragma unroll
;         for (int bj = 0; bj < 2; ++bj)
; #pragma unroll
;           for (int m = 0; m < 4; ++m)
; #pragma unroll
;             for (int n = 0; n < 2; ++n) {
;               int fl = ai * 128 + wr * 64 + m * 16 + fq * 4;
;               int tl = bj * 128 + wc * 32 + n * 16 + fr;
;               f32x4 v = acc[ai][bj][m][n];
;               u32x2 o;
;               o.x = pack2(v[0] * sc, v[1] * sc);
;               o.y = pack2(v[2] * sc, v[3] * sc);
;               *reinterpret_cast<u32x2*>(cl + tl * 512 + (((fl >> 3) ^ (tl & 31)) << 4) + ((fl >> 2) & 1) * 8) = o;
;             }
.LBB0_242:
	s_or_b64 exec, exec, s[14:15]
	s_and_b32 s16, s37, -16
	v_bfe_u32 v133, v146, 6, 2
	s_mov_b64 s[14:15], -1
	s_cmp_eq_u32 s16, 16
	v_or_b32_e32 v132, 16, v97
	s_cbranch_scc1 .LBB0_244
	s_cmp_eq_u32 s11, 8
	s_cselect_b64 vcc, -1, 0
	v_mov_b32_e32 v130, 0x3e0293ee
	v_cndmask_b32_e32 v134, 1.0, v130, vcc
	v_lshlrev_b32_e32 v130, 2, v147
	v_and_or_b32 v135, v130, 8, v148
	v_lshlrev_b32_e32 v130, 3, v147
	v_and_b32_e32 v136, 8, v130
	v_mul_f32_e32 v130, v134, v126
	v_mul_f32_e32 v131, v134, v127
	v_cvt_pk_bf16_f32 v130, v130, v131
	v_mul_f32_e32 v131, v134, v128
	v_mul_f32_e32 v138, v134, v129
	v_lshrrev_b32_e32 v137, 3, v135
	v_cvt_pk_bf16_f32 v131, v131, v138
	v_lshlrev_b32_e32 v138, 14, v133
	v_lshlrev_b32_e32 v139, 9, v97
	v_add3_u32 v138, 32, v138, v139
	v_xor_b32_e32 v139, v137, v97
	v_lshlrev_b32_e32 v139, 4, v139
	v_add3_u32 v140, v138, v139, v136
	ds_write_b64 v140, v[130:131]
	v_mul_f32_e32 v130, v134, v122
	v_mul_f32_e32 v131, v134, v123
	v_cvt_pk_bf16_f32 v130, v130, v131
	v_mul_f32_e32 v131, v134, v124
	v_mul_f32_e32 v140, v134, v125
	v_cvt_pk_bf16_f32 v131, v131, v140
	v_bitop3_b32 v140, v137, v97, 16 bitop3:0x1e
	v_lshlrev_b32_e32 v140, 4, v140
	v_add3_u32 v141, v138, v140, v136
	ds_write_b64 v141, v[130:131] offset:8192
	v_mul_f32_e32 v130, v134, v118
	v_mul_f32_e32 v131, v134, v119
	v_cvt_pk_bf16_f32 v130, v130, v131
	v_mul_f32_e32 v131, v134, v120
	v_mul_f32_e32 v141, v134, v121
	v_cvt_pk_bf16_f32 v131, v131, v141
	v_bitop3_b32 v141, v137, v97, 2 bitop3:0x36
	v_lshlrev_b32_e32 v141, 4, v141
	v_add3_u32 v142, v138, v141, v136
	ds_write_b64 v142, v[130:131]
	v_mul_f32_e32 v130, v134, v114
	v_mul_f32_e32 v131, v134, v115
	v_cvt_pk_bf16_f32 v130, v130, v131
	v_mul_f32_e32 v131, v134, v116
	v_mul_f32_e32 v142, v134, v117
	v_cvt_pk_bf16_f32 v131, v131, v142
	v_bitop3_b32 v142, v137, v132, 2 bitop3:0x36
	v_lshlrev_b32_e32 v142, 4, v142
	v_add3_u32 v143, v138, v142, v136
	ds_write_b64 v143, v[130:131] offset:8192
	v_mul_f32_e32 v130, v134, v110
	v_mul_f32_e32 v131, v134, v111
	v_cvt_pk_bf16_f32 v130, v130, v131
	v_mul_f32_e32 v131, v134, v112
	v_mul_f32_e32 v143, v134, v113
	v_cvt_pk_bf16_f32 v131, v131, v143
	v_bitop3_b32 v143, v137, v97, 4 bitop3:0x36
	v_lshlrev_b32_e32 v143, 4, v143
	v_add3_u32 v144, v138, v143, v136
	ds_write_b64 v144, v[130:131]
	v_mul_f32_e32 v130, v134, v106
	v_mul_f32_e32 v131, v134, v107
	v_cvt_pk_bf16_f32 v130, v130, v131
	v_mul_f32_e32 v131, v134, v108
	v_mul_f32_e32 v144, v134, v109
	v_cvt_pk_bf16_f32 v131, v131, v144
	v_bitop3_b32 v144, v137, v132, 4 bitop3:0x36
	v_lshlrev_b32_e32 v144, 4, v144
	v_add3_u32 v145, v138, v144, v136
	ds_write_b64 v145, v[130:131] offset:8192
	v_mul_f32_e32 v130, v134, v102
	v_mul_f32_e32 v131, v134, v103
	v_cvt_pk_bf16_f32 v130, v130, v131
	v_mul_f32_e32 v131, v134, v104
	v_mul_f32_e32 v145, v134, v105
	v_cvt_pk_bf16_f32 v131, v131, v145
	v_bitop3_b32 v145, v137, v97, 6 bitop3:0x36
	v_lshlrev_b32_e32 v145, 4, v145
	v_add3_u32 v150, v138, v145, v136
	ds_write_b64 v150, v[130:131]
	v_mul_f32_e32 v130, v134, v98
	v_mul_f32_e32 v131, v134, v99
	v_bitop3_b32 v137, v137, v132, 6 bitop3:0x36
	v_cvt_pk_bf16_f32 v130, v130, v131
	v_mul_f32_e32 v131, v134, v100
	v_mul_f32_e32 v150, v134, v101
	v_lshlrev_b32_e32 v137, 4, v137
	v_cvt_pk_bf16_f32 v131, v131, v150
	v_add3_u32 v150, v138, v137, v136
	ds_write_b64 v150, v[130:131] offset:8192
	v_mul_f32_e32 v130, v134, v92
	v_mul_f32_e32 v131, v134, v93
	v_cvt_pk_bf16_f32 v130, v130, v131
	v_mul_f32_e32 v131, v134, v94
	v_mul_f32_e32 v150, v134, v95
	v_cvt_pk_bf16_f32 v131, v131, v150
	v_add_u32_e32 v150, 0x10000, v138
	v_add3_u32 v139, v150, v139, v136
	ds_write_b64 v139, v[130:131]
	v_mul_f32_e32 v130, v134, v88
	v_mul_f32_e32 v131, v134, v89
	v_cvt_pk_bf16_f32 v130, v130, v131
	v_mul_f32_e32 v131, v134, v90
	v_mul_f32_e32 v139, v134, v91
	v_cvt_pk_bf16_f32 v131, v131, v139
	v_add_u32_e32 v139, 0x12000, v138
	v_add3_u32 v140, v139, v140, v136
	ds_write_b64 v140, v[130:131]
	v_mul_f32_e32 v130, v134, v84
	v_mul_f32_e32 v131, v134, v85
	v_cvt_pk_bf16_f32 v130, v130, v131
	v_mul_f32_e32 v131, v134, v86
	v_mul_f32_e32 v140, v134, v87
	v_cvt_pk_bf16_f32 v131, v131, v140
	v_add3_u32 v140, v150, v141, v136
	ds_write_b64 v140, v[130:131]
	v_mul_f32_e32 v130, v134, v80
	v_mul_f32_e32 v131, v134, v81
	v_cvt_pk_bf16_f32 v130, v130, v131
	v_mul_f32_e32 v131, v134, v82
	v_mul_f32_e32 v140, v134, v83
	v_cvt_pk_bf16_f32 v131, v131, v140
	v_add3_u32 v140, v139, v142, v136
	ds_write_b64 v140, v[130:131]
	v_mul_f32_e32 v130, v134, v76
	v_mul_f32_e32 v131, v134, v77
	v_cvt_pk_bf16_f32 v130, v130, v131
	v_mul_f32_e32 v131, v134, v78
	v_mul_f32_e32 v140, v134, v79
	v_cvt_pk_bf16_f32 v131, v131, v140
	v_add3_u32 v140, v150, v143, v136
	ds_write_b64 v140, v[130:131]
	v_mul_f32_e32 v130, v134, v72
	v_mul_f32_e32 v131, v134, v73
	v_cvt_pk_bf16_f32 v130, v130, v131
	v_mul_f32_e32 v131, v134, v74
	v_mul_f32_e32 v140, v134, v75
	v_cvt_pk_bf16_f32 v131, v131, v140
	v_add3_u32 v140, v139, v144, v136
	ds_write_b64 v140, v[130:131]
	v_mul_f32_e32 v130, v134, v68
	v_mul_f32_e32 v131, v134, v69
	v_cvt_pk_bf16_f32 v130, v130, v131
	v_mul_f32_e32 v131, v134, v70
	v_mul_f32_e32 v140, v134, v71
	v_cvt_pk_bf16_f32 v131, v131, v140
	v_add3_u32 v140, v150, v145, v136
	ds_write_b64 v140, v[130:131]
	v_mul_f32_e32 v130, v134, v64
	v_mul_f32_e32 v131, v134, v65
	v_cvt_pk_bf16_f32 v130, v130, v131
	v_mul_f32_e32 v131, v134, v66
	v_add3_u32 v137, v139, v137, v136
	v_mul_f32_e32 v140, v134, v67
	v_cvt_pk_bf16_f32 v131, v131, v140
	ds_write_b64 v137, v[130:131]
	v_add_u32_e32 v130, 0x80, v135
	v_lshrrev_b32_e32 v137, 3, v130
	v_mul_f32_e32 v130, v134, v60
; __device__ __forceinline__ void phase_gemm1(const Params& p, int layer, int rep) {
;     ...
;               int fl = ai * 128 + wr * 64 + m * 16 + fq * 4;
;               int tl = bj * 128 + wc * 32 + n * 16 + fr;
;               f32x4 v = acc[ai][bj][m][n];
;               u32x2 o;
;               o.x = pack2(v[0] * sc, v[1] * sc);
;               o.y = pack2(v[2] * sc, v[3] * sc);
;               *reinterpret_cast<u32x2*>(cl + tl * 512 + (((fl >> 3) ^ (tl & 31)) << 4) + ((fl >> 2) & 1) * 8) = o;
;             }
;       __syncthreads();
;       u32x4 cv[16];
; #pragma unroll
;       for (int i = 0; i < 16; ++i) {
;         int id = i * NTHR + tidx, tl = id >> 5, ch = id & 31;
;         cv[i] = *reinterpret_cast<const u32x4*>(cl + tl * 512 + ((ch ^ (tl & 31)) << 4));
	v_mul_f32_e32 v131, v134, v61
	v_cvt_pk_bf16_f32 v130, v130, v131
	v_mul_f32_e32 v131, v134, v62
	v_mul_f32_e32 v140, v134, v63
	v_cvt_pk_bf16_f32 v131, v131, v140
	v_xor_b32_e32 v140, v137, v97
	v_lshlrev_b32_e32 v140, 4, v140
	v_add3_u32 v141, v138, v140, v136
	ds_write_b64 v141, v[130:131]
	v_mul_f32_e32 v130, v134, v56
	v_mul_f32_e32 v131, v134, v57
	v_bitop3_b32 v137, v137, v97, 16 bitop3:0x1e
	v_cvt_pk_bf16_f32 v130, v130, v131
	v_mul_f32_e32 v131, v134, v58
	v_mul_f32_e32 v141, v134, v59
	v_lshlrev_b32_e32 v137, 4, v137
	v_cvt_pk_bf16_f32 v131, v131, v141
	v_add3_u32 v141, v138, v137, v136
	ds_write_b64 v141, v[130:131] offset:8192
	v_add_u32_e32 v130, 0x90, v135
	v_lshrrev_b32_e32 v141, 3, v130
	v_mul_f32_e32 v130, v134, v52
	v_mul_f32_e32 v131, v134, v53
	v_cvt_pk_bf16_f32 v130, v130, v131
	v_mul_f32_e32 v131, v134, v54
	v_mul_f32_e32 v142, v134, v55
	v_cvt_pk_bf16_f32 v131, v131, v142
	v_xor_b32_e32 v142, v141, v97
	v_lshlrev_b32_e32 v142, 4, v142
	v_add3_u32 v143, v138, v142, v136
	ds_write_b64 v143, v[130:131]
	v_mul_f32_e32 v130, v134, v48
	v_mul_f32_e32 v131, v134, v49
	v_bitop3_b32 v141, v141, v97, 16 bitop3:0x1e
	v_cvt_pk_bf16_f32 v130, v130, v131
	v_mul_f32_e32 v131, v134, v50
	v_mul_f32_e32 v143, v134, v51
	v_lshlrev_b32_e32 v141, 4, v141
	v_cvt_pk_bf16_f32 v131, v131, v143
	v_add3_u32 v143, v138, v141, v136
	ds_write_b64 v143, v[130:131] offset:8192
	v_add_u32_e32 v130, 0xa0, v135
	v_lshrrev_b32_e32 v143, 3, v130
	v_mul_f32_e32 v130, v134, v44
	v_mul_f32_e32 v131, v134, v45
	v_cvt_pk_bf16_f32 v130, v130, v131
	v_mul_f32_e32 v131, v134, v46
	v_mul_f32_e32 v144, v134, v47
	v_cvt_pk_bf16_f32 v131, v131, v144
	v_xor_b32_e32 v144, v143, v97
	v_lshlrev_b32_e32 v144, 4, v144
	v_add3_u32 v145, v138, v144, v136
	ds_write_b64 v145, v[130:131]
	v_mul_f32_e32 v130, v134, v40
	v_mul_f32_e32 v131, v134, v41
	v_bitop3_b32 v143, v143, v97, 16 bitop3:0x1e
	v_cvt_pk_bf16_f32 v130, v130, v131
	v_mul_f32_e32 v131, v134, v42
	v_mul_f32_e32 v145, v134, v43
	v_lshlrev_b32_e32 v143, 4, v143
	v_cvt_pk_bf16_f32 v131, v131, v145
	v_add3_u32 v145, v138, v143, v136
	ds_write_b64 v145, v[130:131] offset:8192
	v_add_u32_e32 v130, 0xb0, v135
	v_lshrrev_b32_e32 v135, 3, v130
	v_mul_f32_e32 v130, v134, v36
	v_mul_f32_e32 v131, v134, v37
	v_cvt_pk_bf16_f32 v130, v130, v131
	v_mul_f32_e32 v131, v134, v38
	v_mul_f32_e32 v145, v134, v39
	v_cvt_pk_bf16_f32 v131, v131, v145
	v_xor_b32_e32 v145, v135, v97
	v_lshlrev_b32_e32 v145, 4, v145
	v_add3_u32 v151, v138, v145, v136
	ds_write_b64 v151, v[130:131]
	v_mul_f32_e32 v130, v134, v32
	v_mul_f32_e32 v131, v134, v33
	v_bitop3_b32 v135, v135, v97, 16 bitop3:0x1e
	v_cvt_pk_bf16_f32 v130, v130, v131
	v_mul_f32_e32 v131, v134, v34
	v_lshlrev_b32_e32 v135, 4, v135
	v_mul_f32_e32 v151, v134, v35
	v_cvt_pk_bf16_f32 v131, v131, v151
	v_add3_u32 v138, v138, v135, v136
	ds_write_b64 v138, v[130:131] offset:8192
	v_mul_f32_e32 v130, v134, v28
	v_mul_f32_e32 v131, v134, v29
	v_cvt_pk_bf16_f32 v130, v130, v131
	v_mul_f32_e32 v131, v134, v30
	v_mul_f32_e32 v138, v134, v31
	v_cvt_pk_bf16_f32 v131, v131, v138
	v_add3_u32 v138, v150, v140, v136
	ds_write_b64 v138, v[130:131]
	v_mul_f32_e32 v130, v134, v24
	v_mul_f32_e32 v131, v134, v25
	v_cvt_pk_bf16_f32 v130, v130, v131
	v_mul_f32_e32 v131, v134, v26
	v_mul_f32_e32 v138, v134, v27
	v_cvt_pk_bf16_f32 v131, v131, v138
	v_add3_u32 v137, v139, v137, v136
	ds_write_b64 v137, v[130:131]
	v_mul_f32_e32 v130, v134, v20
	v_mul_f32_e32 v131, v134, v21
	v_cvt_pk_bf16_f32 v130, v130, v131
	v_mul_f32_e32 v131, v134, v22
	v_mul_f32_e32 v137, v134, v23
	v_cvt_pk_bf16_f32 v131, v131, v137
	v_add3_u32 v137, v150, v142, v136
	ds_write_b64 v137, v[130:131]
	v_mul_f32_e32 v130, v134, v16
	v_mul_f32_e32 v131, v134, v17
	v_cvt_pk_bf16_f32 v130, v130, v131
	v_mul_f32_e32 v131, v134, v18
	v_mul_f32_e32 v137, v134, v19
	v_cvt_pk_bf16_f32 v131, v131, v137
	v_add3_u32 v137, v139, v141, v136
	ds_write_b64 v137, v[130:131]
	v_mul_f32_e32 v130, v134, v12
	v_mul_f32_e32 v131, v134, v13
	v_cvt_pk_bf16_f32 v130, v130, v131
	v_mul_f32_e32 v131, v134, v14
	v_mul_f32_e32 v137, v134, v15
	v_cvt_pk_bf16_f32 v131, v131, v137
	v_add3_u32 v137, v150, v144, v136
	ds_write_b64 v137, v[130:131]
	v_mul_f32_e32 v130, v134, v8
	v_mul_f32_e32 v131, v134, v9
	v_cvt_pk_bf16_f32 v130, v130, v131
	v_mul_f32_e32 v131, v134, v10
	v_mul_f32_e32 v137, v134, v11
	v_cvt_pk_bf16_f32 v131, v131, v137
	v_add3_u32 v137, v139, v143, v136
	ds_write_b64 v137, v[130:131]
	v_mul_f32_e32 v130, v134, v4
	v_mul_f32_e32 v131, v134, v5
	v_cvt_pk_bf16_f32 v130, v130, v131
	v_mul_f32_e32 v131, v134, v6
	v_mul_f32_e32 v137, v134, v7
	v_cvt_pk_bf16_f32 v131, v131, v137
	v_add3_u32 v137, v150, v145, v136
	ds_write_b64 v137, v[130:131]
	v_mul_f32_e32 v130, v134, v0
	v_mul_f32_e32 v131, v134, v1
	v_cvt_pk_bf16_f32 v130, v130, v131
	v_mul_f32_e32 v131, v134, v2
	v_mul_f32_e32 v134, v134, v3
	v_cvt_pk_bf16_f32 v131, v131, v134
	v_add3_u32 v134, v139, v135, v136
	v_ashrrev_i32_e32 v204, 5, v146
	ds_write_b64 v134, v[130:131]
	v_xor_b32_e32 v131, v204, v146
	v_lshlrev_b32_e32 v131, 4, v131
	v_lshlrev_b32_e32 v130, 9, v204
	v_and_b32_e32 v131, 0x1f0, v131
	v_add3_u32 v130, 32, v130, v131
	v_add_u32_e32 v131, 0x200, v146
	v_ashrrev_i32_e32 v206, 5, v131
	v_xor_b32_e32 v134, v206, v146
	v_lshlrev_b32_e32 v134, 4, v134
	v_lshlrev_b32_e32 v131, 9, v206
	v_and_b32_e32 v134, 0x1f0, v134
	s_waitcnt vmcnt(0) lgkmcnt(0)
	s_barrier
; __device__ __forceinline__ void phase_gemm1(const Params& p, int layer, int rep) {
;     ...
;       for (int i = 0; i < 16; ++i) {
;         int id = i * NTHR + tidx, tl = id >> 5, ch = id & 31;
;         cv[i] = *reinterpret_cast<const u32x4*>(cl + tl * 512 + ((ch ^ (tl & 31)) << 4));
;       }
; #pragma unroll
;       for (int i = 0; i < 16; ++i) {
;         int id = i * NTHR + tidx, tl = id >> 5, ch = id & 31;
;         *reinterpret_cast<u32x4*>(proj + (size_t)(tok0 + tl) * DIN + feat0 + ch * 8) = cv[i];
;       }
	v_add3_u32 v131, 32, v131, v134
	ds_read_b128 v[134:137], v130
	ds_read_b128 v[138:141], v131
	v_add_u32_e32 v130, 0x400, v146
	v_ashrrev_i32_e32 v207, 5, v130
	v_xor_b32_e32 v131, v207, v146
	v_lshlrev_b32_e32 v131, 4, v131
	v_lshlrev_b32_e32 v130, 9, v207
	v_and_b32_e32 v131, 0x1f0, v131
	v_add3_u32 v130, 32, v130, v131
	v_add_u32_e32 v131, 0x600, v146
	v_ashrrev_i32_e32 v208, 5, v131
	v_xor_b32_e32 v142, v208, v146
	v_lshlrev_b32_e32 v142, 4, v142
	v_lshlrev_b32_e32 v131, 9, v208
	v_and_b32_e32 v142, 0x1f0, v142
	v_add3_u32 v131, 32, v131, v142
	ds_read_b128 v[142:145], v130
	ds_read_b128 v[150:153], v131
	v_add_u32_e32 v130, 0x800, v146
	v_ashrrev_i32_e32 v209, 5, v130
	v_xor_b32_e32 v131, v209, v146
	v_lshlrev_b32_e32 v131, 4, v131
	v_lshlrev_b32_e32 v130, 9, v209
	v_and_b32_e32 v131, 0x1f0, v131
	v_add3_u32 v130, 32, v130, v131
	v_add_u32_e32 v131, 0xa00, v146
	v_ashrrev_i32_e32 v212, 5, v131
	v_xor_b32_e32 v154, v212, v146
	v_lshlrev_b32_e32 v154, 4, v154
	v_lshlrev_b32_e32 v131, 9, v212
	v_and_b32_e32 v154, 0x1f0, v154
	v_add3_u32 v131, 32, v131, v154
	ds_read_b128 v[154:157], v130
	ds_read_b128 v[158:161], v131
	v_add_u32_e32 v130, 0xc00, v146
	v_ashrrev_i32_e32 v213, 5, v130
	v_xor_b32_e32 v131, v213, v146
	v_lshlrev_b32_e32 v131, 4, v131
	v_lshlrev_b32_e32 v130, 9, v213
	v_and_b32_e32 v131, 0x1f0, v131
	v_add3_u32 v130, 32, v130, v131
	v_add_u32_e32 v131, 0xe00, v146
	v_ashrrev_i32_e32 v216, 5, v131
	v_xor_b32_e32 v162, v216, v146
	v_lshlrev_b32_e32 v162, 4, v162
	v_lshlrev_b32_e32 v131, 9, v216
	v_and_b32_e32 v162, 0x1f0, v162
	v_add3_u32 v131, 32, v131, v162
	ds_read_b128 v[164:167], v130
	ds_read_b128 v[168:171], v131
	v_add_u32_e32 v130, 0x1000, v146
	v_ashrrev_i32_e32 v217, 5, v130
	v_xor_b32_e32 v131, v217, v146
	v_lshlrev_b32_e32 v131, 4, v131
	v_lshlrev_b32_e32 v130, 9, v217
	v_and_b32_e32 v131, 0x1f0, v131
	v_add3_u32 v130, 32, v130, v131
	v_add_u32_e32 v131, 0x1200, v146
	v_ashrrev_i32_e32 v218, 5, v131
	v_xor_b32_e32 v162, v218, v146
	v_lshlrev_b32_e32 v162, 4, v162
	v_lshlrev_b32_e32 v131, 9, v218
	v_and_b32_e32 v162, 0x1f0, v162
	v_add3_u32 v131, 32, v131, v162
	ds_read_b128 v[172:175], v130
	ds_read_b128 v[176:179], v131
	v_add_u32_e32 v130, 0x1400, v146
	v_ashrrev_i32_e32 v219, 5, v130
	v_xor_b32_e32 v131, v219, v146
	v_lshlrev_b32_e32 v131, 4, v131
	v_lshlrev_b32_e32 v130, 9, v219
	v_and_b32_e32 v131, 0x1f0, v131
	v_add3_u32 v130, 32, v130, v131
	v_add_u32_e32 v131, 0x1600, v146
	v_ashrrev_i32_e32 v222, 5, v131
	v_xor_b32_e32 v162, v222, v146
	v_lshlrev_b32_e32 v162, 4, v162
	v_lshlrev_b32_e32 v131, 9, v222
	v_and_b32_e32 v162, 0x1f0, v162
	v_add3_u32 v131, 32, v131, v162
	ds_read_b128 v[180:183], v130
	ds_read_b128 v[184:187], v131
	v_add_u32_e32 v130, 0x1800, v146
	v_ashrrev_i32_e32 v223, 5, v130
	v_xor_b32_e32 v131, v223, v146
	v_lshlrev_b32_e32 v131, 4, v131
	v_lshlrev_b32_e32 v130, 9, v223
	v_and_b32_e32 v131, 0x1f0, v131
	v_add3_u32 v130, 32, v130, v131
	v_add_u32_e32 v131, 0x1a00, v146
	v_ashrrev_i32_e32 v224, 5, v131
	v_xor_b32_e32 v162, v224, v146
	v_lshlrev_b32_e32 v162, 4, v162
	v_lshlrev_b32_e32 v131, 9, v224
	v_and_b32_e32 v162, 0x1f0, v162
	v_add3_u32 v131, 32, v131, v162
	ds_read_b128 v[188:191], v130
	ds_read_b128 v[192:195], v131
	v_add_u32_e32 v130, 0x1c00, v146
	v_ashrrev_i32_e32 v225, 5, v130
	v_xor_b32_e32 v131, v225, v146
	v_lshlrev_b32_e32 v131, 4, v131
	v_lshlrev_b32_e32 v130, 9, v225
	v_and_b32_e32 v131, 0x1f0, v131
	v_add3_u32 v130, 32, v130, v131
	v_add_u32_e32 v131, 0x1e00, v146
	v_ashrrev_i32_e32 v226, 5, v131
	v_xor_b32_e32 v162, v226, v146
	s_ashr_i32 s11, s10, 31
	v_lshlrev_b32_e32 v162, 4, v162
	s_lshl_b64 s[14:15], s[10:11], 1
	v_lshlrev_b32_e32 v131, 9, v226
	v_and_b32_e32 v162, 0x1f0, v162
	s_add_u32 s14, s30, s14
	v_add3_u32 v131, 32, v131, v162
	s_addc_u32 s15, s31, s15
	v_and_b32_e32 v162, 0x1f0, v149
	ds_read_b128 v[196:199], v130
	ds_read_b128 v[200:203], v131
	v_lshl_add_u64 v[130:131], s[14:15], 0, v[162:163]
	v_add_u32_e32 v149, s35, v204
	v_mad_i64_i32 v[204:205], s[14:15], v149, s63, v[130:131]
	s_waitcnt lgkmcnt(14)
	s_sleep 32
	global_store_dwordx4 v[204:205], v[134:137], off
	s_nop 1
	v_add_u32_e32 v134, s35, v206
	v_mad_i64_i32 v[134:135], s[14:15], v134, s63, v[130:131]
	global_store_dwordx4 v[134:135], v[138:141], off
	v_add_u32_e32 v134, s35, v207
	v_mad_i64_i32 v[134:135], s[14:15], v134, s63, v[130:131]
	s_waitcnt lgkmcnt(13)
	global_store_dwordx4 v[134:135], v[142:145], off
	v_add_u32_e32 v134, s35, v208
	v_mad_i64_i32 v[134:135], s[14:15], v134, s63, v[130:131]
	s_waitcnt lgkmcnt(12)
	global_store_dwordx4 v[134:135], v[150:153], off
	v_add_u32_e32 v134, s35, v209
	v_mad_i64_i32 v[134:135], s[14:15], v134, s63, v[130:131]
	s_waitcnt lgkmcnt(11)
	global_store_dwordx4 v[134:135], v[154:157], off
	v_add_u32_e32 v134, s35, v212
	v_mad_i64_i32 v[134:135], s[14:15], v134, s63, v[130:131]
	s_waitcnt lgkmcnt(10)
	global_store_dwordx4 v[134:135], v[158:161], off
	v_add_u32_e32 v134, s35, v213
	v_mad_i64_i32 v[134:135], s[14:15], v134, s63, v[130:131]
	s_waitcnt lgkmcnt(9)
	global_store_dwordx4 v[134:135], v[164:167], off
	v_add_u32_e32 v134, s35, v216
	v_mad_i64_i32 v[134:135], s[14:15], v134, s63, v[130:131]
	s_waitcnt lgkmcnt(8)
	global_store_dwordx4 v[134:135], v[168:171], off
	v_add_u32_e32 v134, s35, v217
	v_mad_i64_i32 v[134:135], s[14:15], v134, s63, v[130:131]
	s_waitcnt lgkmcnt(7)
	global_store_dwordx4 v[134:135], v[172:175], off
	v_add_u32_e32 v134, s35, v218
	v_mad_i64_i32 v[134:135], s[14:15], v134, s63, v[130:131]
	s_waitcnt lgkmcnt(6)
	global_store_dwordx4 v[134:135], v[176:179], off
	v_add_u32_e32 v134, s35, v219
	v_mad_i64_i32 v[134:135], s[14:15], v134, s63, v[130:131]
	s_waitcnt lgkmcnt(5)
	global_store_dwordx4 v[134:135], v[180:183], off
	v_add_u32_e32 v134, s35, v222
	v_mad_i64_i32 v[134:135], s[14:15], v134, s63, v[130:131]
	s_waitcnt lgkmcnt(4)
	global_store_dwordx4 v[134:135], v[184:187], off
	v_add_u32_e32 v134, s35, v223
	v_mad_i64_i32 v[134:135], s[14:15], v134, s63, v[130:131]
	s_waitcnt lgkmcnt(3)
	global_store_dwordx4 v[134:135], v[188:191], off
	v_add_u32_e32 v134, s35, v224
	v_mad_i64_i32 v[134:135], s[14:15], v134, s63, v[130:131]
	s_waitcnt lgkmcnt(2)
	global_store_dwordx4 v[134:135], v[192:195], off
	v_add_u32_e32 v134, s35, v225
	v_mad_i64_i32 v[134:135], s[14:15], v134, s63, v[130:131]
	s_waitcnt lgkmcnt(1)
	global_store_dwordx4 v[134:135], v[196:199], off
	v_add_u32_e32 v134, s35, v226
	v_mad_i64_i32 v[130:131], s[14:15], v134, s63, v[130:131]
	s_mov_b64 s[14:15], 0
	s_waitcnt lgkmcnt(0)
	global_store_dwordx4 v[130:131], v[200:203], off
